# stack_i + GEMM phase prologues de-serialised: K-tile 1 staging loads issued before the first wait/barrier (vmcnt(2) -> vmcnt(8))
# baseline (speedup 1.0000x reference)
; #define PG8_STAGE(bufoff, gbase, voff) do { const int so_ = (int)(unsigned)((const char*)(gbase) - base_##voff); _Pragma("unroll") for (int _i = 0; _i < 2; ++_i) \
;         __builtin_amdgcn_raw_ptr_buffer_load_lds(rs_##voff, (PG8_LAS unsigned*)(lds + (bufoff) + ldsw + _i * 8192), 16, (int)(voff)[_i], so_, 0, 0); } while (0)
; #define PG8_WAIT_V(n) asm volatile("s_waitcnt vmcnt(" #n ")" ::: "memory")
; #define PG8_BAR __builtin_amdgcn_s_barrier()
; template <class Epi, class Sched, bool ALIGN_EPI = false, bool SP2 = false>
; __device__ __forceinline__ void gemm_phase(PG8_LAS unsigned char* lds, const Gemm g, const Sched& S, const Epi& E, int tid_in) {
;     int tid_ = tid_in; asm volatile("" : "+v"(tid_)); const int tid = tid_, wid = __builtin_amdgcn_readfirstlane(tid >> 6), lane = tid & 63, wr = wid >> 2, wc = wid & 3, fr = lane & 15, fq = lane >> 4;
;     const int K = g.K, nt = K / BK;
;     unsigned voffA[2], voffB[2];
; #pragma unroll
;     for (int i = 0; i < 2; ++i) { int R, C; stage_rc(tid * 16 + i * 8192, R, C); const int Rb = Epi::PERM ? ((R & ~31) + perm32(R & 31)) : R;
;         voffA[i] = (unsigned)(R * g.lda + C) * 2u; voffB[i] = (unsigned)(Rb * g.ldb + C) * 2u; }
;     const char* const base_voffA = (const char*)g.A; const char* const base_voffB = (const char*)g.Bt;
;     const __amdgpu_buffer_rsrc_t rs_voffA = __builtin_amdgcn_make_buffer_rsrc((void*)g.A, 0, 0x7fffffff, 0x00020000), rs_voffB = __builtin_amdgcn_make_buffer_rsrc((void*)g.Bt, 0, 0x7fffffff, 0x00020000);
;     const size_t kstep = (size_t)(BK * 2);
;     const size_t hstepA = (size_t)HALF * g.lda * 2, hstepB = (size_t)HALF * g.ldb * 2;
;     const size_t tstepA = 2 * hstepA, tstepB = 2 * hstepB;
;     const unsigned ldsw = (unsigned)wid * 1024u;
;     const int aoff = lds_byte(wr * 64 + fr, fq * 8), boff = lds_byte(wc * 32 + fr, fq * 8);
;     ...
;     if constexpr (SP2) {
;         PG8_STAGE(PG8_SB(0, 0), cB, voffB); PG8_STAGE(PG8_SB(0, 1), cB + hstepB, voffB); PG8_STAGE(PG8_SA(0, 0), cA, voffA); PG8_STAGE(PG8_SA(0, 1), cA + hstepA, voffA);
;         if (wr == 1) PG8_BAR;
;         PG8_WAIT_V(2); PG8_BAR;
;         PG8_STAGE(PG8_SB(1, 0), cB + kstep, voffB); PG8_STAGE(PG8_SA(1, 0), cA + kstep, voffA); PG8_STAGE(PG8_SB(1, 1), cB + hstepB + kstep, voffB);
;         PG8_WAIT_V(6); PG8_BAR;
.LBB0_306:
	v_readlane_b32 s12, v254, 31
	v_readlane_b32 s13, v254, 32
	s_add_u32 s16, s40, s12
	s_addc_u32 s17, s60, s13
	v_readlane_b32 s12, v254, 28
	v_readlane_b32 s13, v254, 29
	s_add_u32 s12, s4, s12
	s_addc_u32 s13, s26, s13
	s_and_b32 s14, s14, 3
	s_lshl_b32 s18, s15, 13
	s_lshl_b32 s19, s14, 12
	s_add_u32 s38, s10, 0x2f500000
	s_addc_u32 s39, s11, 0
	s_add_u32 s44, s10, 0x24d00000
	v_readlane_b32 s76, v252, 0
	s_addc_u32 s45, s11, 0
	s_mul_i32 s11, s52, 0x6000
	v_readlane_b32 s84, v252, 8
	s_mul_hi_u32 s10, s52, 0x6000
	v_readlane_b32 s85, v252, 9
	s_add_u32 s46, s84, s11
	s_addc_u32 s47, s85, s10
	s_add_i32 s75, s53, 0x18000
	v_readlane_b32 s77, v252, 1
	s_mov_b32 s42, s6
	s_mov_b32 s43, s7
	s_mov_b32 m0, s75
	v_readlane_b32 s10, v254, 27
	s_add_i32 s76, s53, 0x1a000
	v_readlane_b32 s78, v252, 2
	s_add_i32 s77, s53, 0x8000
	s_nop 0
	buffer_load_dwordx4 v207, s[40:43], s10 offen lds
	s_mov_b32 m0, s76
	v_readlane_b32 s79, v252, 3
	buffer_load_dwordx4 v224, s[40:43], s10 offen lds
	s_mov_b32 m0, s77
	v_readlane_b32 s10, v254, 30
	s_add_i32 s78, s53, 0xa000
	s_add_i32 s79, s53, 0x1c000
	s_add_i32 s68, s53, 0x1e000
	v_bfe_u32 v2, v16, 4, 2
	v_and_b32_e32 v0, 15, v16
	buffer_load_dwordx4 v195, s[4:7], s10 offen lds
	s_mov_b32 m0, s78
	v_lshlrev_b32_e32 v4, 4, v2
	buffer_load_dwordx4 v211, s[4:7], s10 offen lds
	s_mov_b32 m0, s79
	v_readlane_b32 s10, v254, 33
	v_lshl_or_b32 v225, s15, 6, v0
	v_lshl_or_b32 v0, v0, 6, v4
	v_lshlrev_b32_e32 v4, 2, v16
	v_readlane_b32 s88, v252, 12
	v_readlane_b32 s89, v252, 13
	buffer_load_dwordx4 v207, s[40:43], s10 offen lds
	s_mov_b32 m0, s68
	v_lshlrev_b32_e32 v3, 3, v2
	buffer_load_dwordx4 v224, s[40:43], s10 offen lds
	v_and_b32_e32 v4, 32, v4
	s_waitcnt vmcnt(8)
	s_barrier
	s_waitcnt vmcnt(6)
	s_add_i32 s69, s53, 0xc000
	v_lshlrev_b32_e32 v2, 2, v2
	v_readlane_b32 s90, v252, 14
	v_readlane_b32 s91, v252, 15
	v_bitop3_b32 v5, v0, s18, v4 bitop3:0xde
	v_bitop3_b32 v0, v0, s19, v4 bitop3:0xde
	s_cmpk_lt_u32 s9, 0x100
	v_lshl_or_b32 v194, s14, 4, v2
	v_readlane_b32 s10, v254, 24
	v_readlane_b32 s88, v252, 54
	v_lshl_or_b32 v236, s14, 5, v3
	s_cselect_b64 s[48:49], -1, 0
	v_or_b32_e32 v206, 64, v194
	s_add_i32 s67, s53, 0xe000
	s_mov_b32 s66, 0
	v_add_u32_e32 v237, 0, v0
	v_add_u32_e32 v238, 0, v5
	v_readlane_b32 s9, v253, 55
	s_mov_b32 s18, s10
	v_readlane_b32 s89, v252, 55
	s_mov_b32 s90, s20
	s_mov_b32 s91, s21
	v_readlane_b32 s80, v252, 4
	v_readlane_b32 s81, v252, 5
	v_readlane_b32 s82, v252, 6
	v_readlane_b32 s83, v252, 7
	v_readlane_b32 s86, v252, 10
	v_readlane_b32 s87, v252, 11
	s_barrier
	v_readlane_b32 s11, v254, 25
	s_branch .LBB0_309

; #define PG8_STAGE(bufoff, gbase, voff) do { const int so_ = (int)(unsigned)((const char*)(gbase) - base_##voff); _Pragma("unroll") for (int _i = 0; _i < 2; ++_i) \
;         __builtin_amdgcn_raw_ptr_buffer_load_lds(rs_##voff, (PG8_LAS unsigned*)(lds + (bufoff) + ldsw + _i * 8192), 16, (int)(voff)[_i], so_, 0, 0); } while (0)
; #define PG8_WAIT_V(n) asm volatile("s_waitcnt vmcnt(" #n ")" ::: "memory")
; #define PG8_BAR __builtin_amdgcn_s_barrier()
; template <class Epi, class Sched, bool ALIGN_EPI = false, bool SP2 = false>
; __device__ __forceinline__ void gemm_phase(PG8_LAS unsigned char* lds, const Gemm g, const Sched& S, const Epi& E, int tid_in) {
;     ...
;     f32x4 acc[2][2][4][2];
; #pragma unroll
;     for (int a = 0; a < 2; ++a)
; #pragma unroll
;         for (int b = 0; b < 2; ++b)
; #pragma unroll
;             for (int m = 0; m < 4; ++m)
; #pragma unroll
;                 for (int n = 0; n < 2; ++n) acc[a][b][m][n] = (f32x4){0.f, 0.f, 0.f, 0.f};
;     ...
;     if constexpr (SP2) {
;         PG8_STAGE(PG8_SB(0, 0), cB, voffB); PG8_STAGE(PG8_SB(0, 1), cB + hstepB, voffB); PG8_STAGE(PG8_SA(0, 0), cA, voffA); PG8_STAGE(PG8_SA(0, 1), cA + hstepA, voffA);
;         if (wr == 1) PG8_BAR;
;         PG8_WAIT_V(2); PG8_BAR;
;         PG8_STAGE(PG8_SB(1, 0), cB + kstep, voffB); PG8_STAGE(PG8_SA(1, 0), cA + kstep, voffA); PG8_STAGE(PG8_SB(1, 1), cB + hstepB + kstep, voffB);
;         PG8_WAIT_V(6); PG8_BAR;
.LBB0_1025:
	v_readlane_b32 s10, v254, 44
	v_readlane_b32 s11, v254, 45
	s_add_u32 s16, s44, s10
	s_addc_u32 s17, s20, s11
	v_readlane_b32 s10, v254, 39
	v_readlane_b32 s24, v254, 34
	s_add_u32 s10, s4, s10
	s_mul_hi_i32 s11, s24, 0x180000
	s_addc_u32 s11, s9, s11
	v_readlane_b32 s12, v254, 37
	v_readlane_b32 s13, v254, 38
	s_add_u32 s12, s10, s12
	s_addc_u32 s13, s11, s13
	s_add_u32 s10, s14, 0x45500000
	s_addc_u32 s11, s15, 0
	s_add_u32 s67, s14, 0x2f504800
	s_addc_u32 s68, s15, 0
	s_add_i32 s69, s21, 0x18000
	s_mov_b32 s46, s6
	s_mov_b32 s47, s7
	s_mov_b32 m0, s69
	v_readlane_b32 s14, v254, 41
	s_add_i32 s71, s21, 0x1a000
	s_add_i32 s72, s21, 0x8000
	s_add_i32 s73, s21, 0xa000
	s_nop 0
	buffer_load_dwordx4 v221, s[44:47], s14 offen lds
	s_mov_b32 m0, s71
	s_add_i32 s74, s21, 0x1c000
	buffer_load_dwordx4 v223, s[44:47], s14 offen lds
	s_mov_b32 m0, s72
	v_readlane_b32 s14, v254, 43
	s_add_i32 s75, s21, 0x1e000
	v_lshrrev_b32_e32 v3, 1, v0
	v_and_b32_e32 v3, 24, v3
	v_and_b32_e32 v2, 15, v0
	v_lshlrev_b32_e32 v4, 1, v3
	buffer_load_dwordx4 v220, s[4:7], s14 offen lds
	s_mov_b32 m0, s73
	v_lshlrev_b32_e32 v0, 2, v0
	buffer_load_dwordx4 v222, s[4:7], s14 offen lds
	s_mov_b32 m0, s74
	v_readlane_b32 s14, v254, 46
	v_lshl_or_b32 v224, s22, 6, v2
	v_lshl_or_b32 v2, v2, 6, v4
	v_and_b32_e32 v0, 32, v0
	s_add_i32 s76, s21, 0xc000
	s_mov_b32 s78, 0
	buffer_load_dwordx4 v221, s[44:47], s14 offen lds
	s_mov_b32 m0, s75
	v_readlane_b32 s34, v254, 15
	buffer_load_dwordx4 v223, s[44:47], s14 offen lds
	s_lshl_b32 s14, s22, 13
	v_bitop3_b32 v4, v2, s14, v0 bitop3:0xde
	s_lshl_b32 s14, s19, 5
	s_and_b32 s19, s14, 0x60
	s_lshl_b32 s14, s19, 7
	v_bitop3_b32 v5, v2, s14, v0 bitop3:0xde
	s_waitcnt vmcnt(8)
	s_barrier
	s_waitcnt vmcnt(6)
	v_or_b32_e32 v225, s19, v3
	v_mov_b32_e32 v2, v1
	v_mov_b32_e32 v3, v1
	s_cmpk_lt_u32 s18, 0x100
	v_mov_b32_e32 v0, v1
	v_add_u32_e32 v236, 0, v5
	v_add_u32_e32 v237, 0, v4
	v_mov_b64_e32 v[6:7], v[2:3]
	v_mov_b64_e32 v[10:11], v[2:3]
	v_mov_b64_e32 v[14:15], v[2:3]
	v_mov_b64_e32 v[18:19], v[2:3]
	v_mov_b64_e32 v[22:23], v[2:3]
	v_mov_b64_e32 v[26:27], v[2:3]
	v_mov_b64_e32 v[30:31], v[2:3]
	v_mov_b64_e32 v[34:35], v[2:3]
	v_mov_b64_e32 v[38:39], v[2:3]
	v_mov_b64_e32 v[42:43], v[2:3]
	v_mov_b64_e32 v[46:47], v[2:3]
	v_mov_b64_e32 v[50:51], v[2:3]
	v_mov_b64_e32 v[54:55], v[2:3]
	v_mov_b64_e32 v[58:59], v[2:3]
	v_mov_b64_e32 v[62:63], v[2:3]
	v_mov_b64_e32 v[66:67], v[2:3]
	v_mov_b64_e32 v[70:71], v[2:3]
	v_mov_b64_e32 v[74:75], v[2:3]
	v_mov_b64_e32 v[78:79], v[2:3]
	v_mov_b64_e32 v[82:83], v[2:3]
	v_mov_b64_e32 v[86:87], v[2:3]
	v_mov_b64_e32 v[90:91], v[2:3]
	v_mov_b64_e32 v[94:95], v[2:3]
	v_mov_b64_e32 v[98:99], v[2:3]
	v_mov_b64_e32 v[102:103], v[2:3]
	v_mov_b64_e32 v[106:107], v[2:3]
	v_mov_b64_e32 v[110:111], v[2:3]
	v_mov_b64_e32 v[114:115], v[2:3]
	v_mov_b64_e32 v[118:119], v[2:3]
	v_mov_b64_e32 v[122:123], v[2:3]
	v_mov_b64_e32 v[126:127], v[2:3]
	v_mov_b64_e32 v[130:131], v[2:3]
	s_cselect_b64 s[14:15], -1, 0
	s_add_i32 s77, s21, 0xe000
	v_mov_b64_e32 v[4:5], v[0:1]
	v_mov_b64_e32 v[8:9], v[0:1]
	v_mov_b64_e32 v[12:13], v[0:1]
	v_mov_b64_e32 v[16:17], v[0:1]
	v_mov_b64_e32 v[20:21], v[0:1]
	v_mov_b64_e32 v[24:25], v[0:1]
	v_mov_b64_e32 v[28:29], v[0:1]
	v_mov_b64_e32 v[32:33], v[0:1]
	v_mov_b64_e32 v[36:37], v[0:1]
	v_mov_b64_e32 v[40:41], v[0:1]
	v_mov_b64_e32 v[44:45], v[0:1]
	v_mov_b64_e32 v[48:49], v[0:1]
	v_mov_b64_e32 v[52:53], v[0:1]
	v_mov_b64_e32 v[56:57], v[0:1]
	v_mov_b64_e32 v[60:61], v[0:1]
	v_mov_b64_e32 v[64:65], v[0:1]
	v_mov_b64_e32 v[68:69], v[0:1]
	v_mov_b64_e32 v[72:73], v[0:1]
	v_mov_b64_e32 v[76:77], v[0:1]
	v_mov_b64_e32 v[80:81], v[0:1]
	v_mov_b64_e32 v[84:85], v[0:1]
	v_mov_b64_e32 v[88:89], v[0:1]
	v_mov_b64_e32 v[92:93], v[0:1]
	v_mov_b64_e32 v[96:97], v[0:1]
	v_mov_b64_e32 v[100:101], v[0:1]
	v_mov_b64_e32 v[104:105], v[0:1]
	v_mov_b64_e32 v[108:109], v[0:1]
	v_mov_b64_e32 v[112:113], v[0:1]
	v_mov_b64_e32 v[116:117], v[0:1]
	v_mov_b64_e32 v[120:121], v[0:1]
	v_mov_b64_e32 v[124:125], v[0:1]
	v_mov_b64_e32 v[128:129], v[0:1]
	s_mov_b32 s35, s24
	v_readlane_b32 s25, v254, 35
	s_barrier
	s_branch .LBB0_1028

; #define PG8_STAGE(bufoff, gbase, voff) do { const int so_ = (int)(unsigned)((const char*)(gbase) - base_##voff); _Pragma("unroll") for (int _i = 0; _i < 2; ++_i) \
;         __builtin_amdgcn_raw_ptr_buffer_load_lds(rs_##voff, (PG8_LAS unsigned*)(lds + (bufoff) + ldsw + _i * 8192), 16, (int)(voff)[_i], so_, 0, 0); } while (0)
; #define PG8_WAIT_V(n) asm volatile("s_waitcnt vmcnt(" #n ")" ::: "memory")
; #define PG8_BAR __builtin_amdgcn_s_barrier()
; template <class Epi, class Sched, bool ALIGN_EPI = false, bool SP2 = false>
; __device__ __forceinline__ void gemm_phase(PG8_LAS unsigned char* lds, const Gemm g, const Sched& S, const Epi& E, int tid_in) {
;     ...
;     f32x4 acc[2][2][4][2];
; #pragma unroll
;     for (int a = 0; a < 2; ++a)
; #pragma unroll
;         for (int b = 0; b < 2; ++b)
; #pragma unroll
;             for (int m = 0; m < 4; ++m)
; #pragma unroll
;                 for (int n = 0; n < 2; ++n) acc[a][b][m][n] = (f32x4){0.f, 0.f, 0.f, 0.f};
;     ...
;     if constexpr (SP2) {
;         PG8_STAGE(PG8_SB(0, 0), cB, voffB); PG8_STAGE(PG8_SB(0, 1), cB + hstepB, voffB); PG8_STAGE(PG8_SA(0, 0), cA, voffA); PG8_STAGE(PG8_SA(0, 1), cA + hstepA, voffA);
;         if (wr == 1) PG8_BAR;
;         PG8_WAIT_V(2); PG8_BAR;
;         PG8_STAGE(PG8_SB(1, 0), cB + kstep, voffB); PG8_STAGE(PG8_SA(1, 0), cA + kstep, voffA); PG8_STAGE(PG8_SB(1, 1), cB + hstepB + kstep, voffB);
;         PG8_WAIT_V(6); PG8_BAR;
.LBB0_1256:
	v_readlane_b32 s12, v254, 1
	v_readlane_b32 s13, v254, 2
	s_add_u32 s12, s40, s12
	s_addc_u32 s10, s34, s13
	v_readlane_b32 s14, v253, 62
	v_readlane_b32 s15, v253, 63
	s_add_u32 s14, s4, s14
	s_addc_u32 s10, s9, s15
	v_and_b32_e32 v163, 15, v162
	v_and_b32_e32 v2, 48, v162
	v_lshlrev_b32_e32 v3, 2, v162
	s_and_b32 s26, s46, 3
	s_lshl_b32 s10, s11, 13
	v_lshl_or_b32 v2, v163, 6, v2
	v_and_b32_e32 v3, 32, v3
	v_bitop3_b32 v4, v2, s10, v3 bitop3:0xde
	s_lshl_b32 s10, s26, 12
	s_add_i32 s68, s35, 0x18000
	v_bitop3_b32 v3, v2, s10, v3 bitop3:0xde
	s_mov_b32 s42, s6
	s_mov_b32 s43, s7
	s_mov_b32 m0, s68
	v_readlane_b32 s10, v253, 61
	s_add_i32 s69, s35, 0x1a000
	s_add_i32 s71, s35, 0x8000
	s_add_i32 s72, s35, 0xa000
	s_nop 0
	buffer_load_dwordx4 v0, s[40:43], s10 offen lds
	s_mov_b32 m0, s69
	s_add_i32 s73, s35, 0x1c000
	buffer_load_dwordx4 v130, s[40:43], s10 offen lds
	s_mov_b32 m0, s71
	v_readlane_b32 s10, v254, 0
	s_add_i32 s74, s35, 0x1e000
	v_mov_b32_e32 v2, 0
	v_readlane_b32 s16, v254, 34
	s_mov_b32 s53, s27
	v_lshl_or_b32 v164, s11, 6, v163
	buffer_load_dwordx4 v0, s[4:7], s10 offen lds
	s_mov_b32 m0, s72
	s_add_i32 s75, s35, 0xc000
	buffer_load_dwordx4 v130, s[4:7], s10 offen lds
	s_mov_b32 m0, s73
	v_readlane_b32 s10, v254, 3
	s_add_i32 s76, s35, 0xe000
	s_mov_b32 s13, 0
	s_sub_i32 s77, 0, s4
	v_add_u32_e32 v131, 0, v3
	v_add_u32_e32 v132, 0, v4
	buffer_load_dwordx4 v0, s[40:43], s10 offen lds
	s_mov_b32 m0, s74
	s_mov_b32 s48, s16
	buffer_load_dwordx4 v130, s[40:43], s10 offen lds
	s_waitcnt vmcnt(8)
	s_barrier
	s_waitcnt vmcnt(6)
	v_readlane_b32 s10, v254, 15
	v_mov_b32_e32 v3, v2
	v_mov_b32_e32 v4, v2
	v_mov_b32_e32 v5, v2
	v_mov_b32_e32 v6, v2
	v_mov_b32_e32 v7, v2
	v_mov_b32_e32 v8, v2
	v_mov_b32_e32 v9, v2
	v_mov_b32_e32 v42, v2
	v_mov_b32_e32 v43, v2
	v_mov_b32_e32 v44, v2
	v_mov_b32_e32 v45, v2
	v_mov_b32_e32 v70, v2
	v_mov_b32_e32 v71, v2
	v_mov_b32_e32 v72, v2
	v_mov_b32_e32 v73, v2
	v_mov_b32_e32 v66, v2
	v_mov_b32_e32 v67, v2
	v_mov_b32_e32 v68, v2
	v_mov_b32_e32 v69, v2
	v_mov_b32_e32 v54, v2
	v_mov_b32_e32 v55, v2
	v_mov_b32_e32 v56, v2
	v_mov_b32_e32 v57, v2
	v_mov_b32_e32 v10, v2
	v_mov_b32_e32 v11, v2
	v_mov_b32_e32 v12, v2
	v_mov_b32_e32 v13, v2
	v_mov_b32_e32 v22, v2
	v_mov_b32_e32 v23, v2
	v_mov_b32_e32 v24, v2
	v_mov_b32_e32 v25, v2
	v_mov_b32_e32 v26, v2
	v_mov_b32_e32 v27, v2
	v_mov_b32_e32 v28, v2
	v_mov_b32_e32 v29, v2
	v_mov_b32_e32 v46, v2
	v_mov_b32_e32 v47, v2
	v_mov_b32_e32 v48, v2
	v_mov_b32_e32 v49, v2
	v_mov_b32_e32 v82, v2
	v_mov_b32_e32 v83, v2
	v_mov_b32_e32 v84, v2
	v_mov_b32_e32 v85, v2
	v_mov_b32_e32 v94, v2
	v_mov_b32_e32 v95, v2
	v_mov_b32_e32 v96, v2
	v_mov_b32_e32 v97, v2
	v_mov_b32_e32 v58, v2
	v_mov_b32_e32 v59, v2
	v_mov_b32_e32 v60, v2
	v_mov_b32_e32 v61, v2
	v_mov_b32_e32 v62, v2
	v_mov_b32_e32 v63, v2
	v_mov_b32_e32 v64, v2
	v_mov_b32_e32 v65, v2
	v_mov_b32_e32 v30, v2
	v_mov_b32_e32 v31, v2
	v_mov_b32_e32 v32, v2
	v_mov_b32_e32 v33, v2
	v_mov_b32_e32 v50, v2
	v_mov_b32_e32 v51, v2
	v_mov_b32_e32 v52, v2
	v_mov_b32_e32 v53, v2
	v_mov_b32_e32 v114, v2
	v_mov_b32_e32 v115, v2
	v_mov_b32_e32 v116, v2
	v_mov_b32_e32 v117, v2
	v_mov_b32_e32 v118, v2
	v_mov_b32_e32 v119, v2
	v_mov_b32_e32 v120, v2
	v_mov_b32_e32 v121, v2
	v_mov_b32_e32 v110, v2
	v_mov_b32_e32 v111, v2
	v_mov_b32_e32 v112, v2
	v_mov_b32_e32 v113, v2
	v_mov_b32_e32 v98, v2
	v_mov_b32_e32 v99, v2
	v_mov_b32_e32 v100, v2
	v_mov_b32_e32 v101, v2
	v_mov_b32_e32 v90, v2
	v_mov_b32_e32 v91, v2
	v_mov_b32_e32 v92, v2
	v_mov_b32_e32 v93, v2
	v_mov_b32_e32 v74, v2
	v_mov_b32_e32 v75, v2
	v_mov_b32_e32 v76, v2
	v_mov_b32_e32 v77, v2
	v_mov_b32_e32 v38, v2
	v_mov_b32_e32 v39, v2
	v_mov_b32_e32 v40, v2
	v_mov_b32_e32 v41, v2
	v_mov_b32_e32 v14, v2
	v_mov_b32_e32 v15, v2
	v_mov_b32_e32 v16, v2
	v_mov_b32_e32 v17, v2
	v_mov_b32_e32 v122, v2
	v_mov_b32_e32 v123, v2
	v_mov_b32_e32 v124, v2
	v_mov_b32_e32 v125, v2
	v_mov_b32_e32 v126, v2
	v_mov_b32_e32 v127, v2
	v_mov_b32_e32 v128, v2
	v_mov_b32_e32 v129, v2
	v_mov_b32_e32 v102, v2
	v_mov_b32_e32 v103, v2
	v_mov_b32_e32 v104, v2
	v_mov_b32_e32 v105, v2
	v_mov_b32_e32 v106, v2
	v_mov_b32_e32 v107, v2
	v_mov_b32_e32 v108, v2
	v_mov_b32_e32 v109, v2
	v_mov_b32_e32 v78, v2
	v_mov_b32_e32 v79, v2
	v_mov_b32_e32 v80, v2
	v_mov_b32_e32 v81, v2
	v_mov_b32_e32 v86, v2
	v_mov_b32_e32 v87, v2
	v_mov_b32_e32 v88, v2
	v_mov_b32_e32 v89, v2
	v_mov_b32_e32 v18, v2
	v_mov_b32_e32 v19, v2
	v_mov_b32_e32 v20, v2
	v_mov_b32_e32 v21, v2
	v_mov_b32_e32 v34, v2
	v_mov_b32_e32 v35, v2
	v_mov_b32_e32 v36, v2
	v_mov_b32_e32 v37, v2
	s_barrier
	v_readlane_b32 s17, v254, 35
	s_branch .LBB0_1258

; #define PG8_STAGE(bufoff, gbase, voff) do { const int so_ = (int)(unsigned)((const char*)(gbase) - base_##voff); _Pragma("unroll") for (int _i = 0; _i < 2; ++_i) \
;         __builtin_amdgcn_raw_ptr_buffer_load_lds(rs_##voff, (PG8_LAS unsigned*)(lds + (bufoff) + ldsw + _i * 8192), 16, (int)(voff)[_i], so_, 0, 0); } while (0)
; #define PG8_WAIT_V(n) asm volatile("s_waitcnt vmcnt(" #n ")" ::: "memory")
; #define PG8_BAR __builtin_amdgcn_s_barrier()
; template <class Epi, class Sched, bool ALIGN_EPI = false, bool SP2 = false>
; __device__ __forceinline__ void gemm_phase(PG8_LAS unsigned char* lds, const Gemm g, const Sched& S, const Epi& E, int tid_in) {
;     int tid_ = tid_in; asm volatile("" : "+v"(tid_)); const int tid = tid_, wid = __builtin_amdgcn_readfirstlane(tid >> 6), lane = tid & 63, wr = wid >> 2, wc = wid & 3, fr = lane & 15, fq = lane >> 4;
;     const int K = g.K, nt = K / BK;
;     unsigned voffA[2], voffB[2];
; #pragma unroll
;     for (int i = 0; i < 2; ++i) { int R, C; stage_rc(tid * 16 + i * 8192, R, C); const int Rb = Epi::PERM ? ((R & ~31) + perm32(R & 31)) : R;
;         voffA[i] = (unsigned)(R * g.lda + C) * 2u; voffB[i] = (unsigned)(Rb * g.ldb + C) * 2u; }
;     const char* const base_voffA = (const char*)g.A; const char* const base_voffB = (const char*)g.Bt;
;     const __amdgpu_buffer_rsrc_t rs_voffA = __builtin_amdgcn_make_buffer_rsrc((void*)g.A, 0, 0x7fffffff, 0x00020000), rs_voffB = __builtin_amdgcn_make_buffer_rsrc((void*)g.Bt, 0, 0x7fffffff, 0x00020000);
;     const size_t kstep = (size_t)(BK * 2);
;     const size_t hstepA = (size_t)HALF * g.lda * 2, hstepB = (size_t)HALF * g.ldb * 2;
;     const size_t tstepA = 2 * hstepA, tstepB = 2 * hstepB;
;     const unsigned ldsw = (unsigned)wid * 1024u;
;     const int aoff = lds_byte(wr * 64 + fr, fq * 8), boff = lds_byte(wc * 32 + fr, fq * 8);
;     ...
;     if constexpr (SP2) {
;         PG8_STAGE(PG8_SB(0, 0), cB, voffB); PG8_STAGE(PG8_SB(0, 1), cB + hstepB, voffB); PG8_STAGE(PG8_SA(0, 0), cA, voffA); PG8_STAGE(PG8_SA(0, 1), cA + hstepA, voffA);
;         if (wr == 1) PG8_BAR;
;         PG8_WAIT_V(2); PG8_BAR;
;         PG8_STAGE(PG8_SB(1, 0), cB + kstep, voffB); PG8_STAGE(PG8_SA(1, 0), cA + kstep, voffA); PG8_STAGE(PG8_SB(1, 1), cB + hstepB + kstep, voffB);
;         PG8_WAIT_V(6); PG8_BAR;
.LBB0_1508:
	v_readlane_b32 s16, v254, 12
	v_readlane_b32 s17, v254, 13
	s_add_u32 s38, s40, s16
	s_addc_u32 s39, s26, s17
	v_readlane_b32 s16, v254, 9
	v_readlane_b32 s17, v254, 10
	s_add_u32 s16, s4, s16
	s_addc_u32 s17, s9, s17
	s_lshl_b32 s14, s14, 5
	s_and_b32 s14, s14, 0x60
	s_lshl_b32 s15, s13, 13
	s_lshl_b32 s18, s14, 7
	s_add_u32 s0, s0, 0x47500000
	s_addc_u32 s1, s1, 0
	s_add_i32 s53, s34, 0x18000
	s_mov_b32 s42, s6
	s_mov_b32 s43, s7
	s_mov_b32 m0, s53
	v_readlane_b32 s19, v254, 8
	s_add_i32 s60, s34, 0x1a000
	s_add_i32 s61, s34, 0x8000
	s_add_i32 s62, s34, 0xa000
	s_nop 0
	buffer_load_dwordx4 v134, s[40:43], s19 offen lds
	s_mov_b32 m0, s60
	s_add_i32 s63, s34, 0x1c000
	buffer_load_dwordx4 v136, s[40:43], s19 offen lds
	s_mov_b32 m0, s61
	v_readlane_b32 s19, v254, 11
	s_add_i32 s66, s34, 0x1e000
	v_lshrrev_b32_e32 v3, 1, v64
	v_and_b32_e32 v3, 24, v3
	v_and_b32_e32 v2, 15, v64
	v_lshlrev_b32_e32 v4, 1, v3
	buffer_load_dwordx4 v0, s[4:7], s19 offen lds
	s_mov_b32 m0, s62
	v_lshl_or_b32 v137, s13, 6, v2
	buffer_load_dwordx4 v135, s[4:7], s19 offen lds
	s_mov_b32 m0, s63
	v_readlane_b32 s19, v254, 14
	v_lshl_or_b32 v2, v2, 6, v4
	v_lshlrev_b32_e32 v4, 2, v64
	v_and_b32_e32 v4, 32, v4
	s_add_i32 s67, s34, 0xc000
	v_bitop3_b32 v5, v2, s15, v4 bitop3:0xde
	buffer_load_dwordx4 v134, s[40:43], s19 offen lds
	s_mov_b32 m0, s66
	v_bitop3_b32 v2, v2, s18, v4 bitop3:0xde
	buffer_load_dwordx4 v136, s[40:43], s19 offen lds
	s_waitcnt vmcnt(8)
	s_barrier
	s_waitcnt vmcnt(6)
	s_cmpk_lt_u32 s12, 0x100
	v_or_b32_e32 v138, s14, v3
	v_readlane_b32 s14, v254, 5
	s_cselect_b64 s[12:13], -1, 0
	s_add_i32 s68, s34, 0xe000
	s_mov_b32 s69, 0
	v_add_u32_e32 v139, 0, v2
	v_add_u32_e32 v140, 0, v5
	v_readlane_b32 s71, v253, 54
	s_mov_b32 s72, s14
	s_barrier
	v_readlane_b32 s15, v254, 6
	s_branch .LBB0_1511

; #define PG8_STAGE(bufoff, gbase, voff) do { const int so_ = (int)(unsigned)((const char*)(gbase) - base_##voff); _Pragma("unroll") for (int _i = 0; _i < 2; ++_i) \
;         __builtin_amdgcn_raw_ptr_buffer_load_lds(rs_##voff, (PG8_LAS unsigned*)(lds + (bufoff) + ldsw + _i * 8192), 16, (int)(voff)[_i], so_, 0, 0); } while (0)
; #define PG8_WAIT_V(n) asm volatile("s_waitcnt vmcnt(" #n ")" ::: "memory")
; #define PG8_BAR __builtin_amdgcn_s_barrier()
; template <class Epi, class Sched, bool ALIGN_EPI = false, bool SP2 = false>
; __device__ __forceinline__ void gemm_phase(PG8_LAS unsigned char* lds, const Gemm g, const Sched& S, const Epi& E, int tid_in) {
;     ...
;     f32x4 acc[2][2][4][2];
; #pragma unroll
;     for (int a = 0; a < 2; ++a)
; #pragma unroll
;         for (int b = 0; b < 2; ++b)
; #pragma unroll
;             for (int m = 0; m < 4; ++m)
; #pragma unroll
;                 for (int n = 0; n < 2; ++n) acc[a][b][m][n] = (f32x4){0.f, 0.f, 0.f, 0.f};
;     ...
;     if constexpr (SP2) {
;         PG8_STAGE(PG8_SB(0, 0), cB, voffB); PG8_STAGE(PG8_SB(0, 1), cB + hstepB, voffB); PG8_STAGE(PG8_SA(0, 0), cA, voffA); PG8_STAGE(PG8_SA(0, 1), cA + hstepA, voffA);
;         if (wr == 1) PG8_BAR;
;         PG8_WAIT_V(2); PG8_BAR;
;         PG8_STAGE(PG8_SB(1, 0), cB + kstep, voffB); PG8_STAGE(PG8_SA(1, 0), cA + kstep, voffA); PG8_STAGE(PG8_SB(1, 1), cB + hstepB + kstep, voffB);
;         PG8_WAIT_V(6); PG8_BAR;
.LBB0_1571:
	v_readlane_b32 s10, v254, 21
	s_add_u32 s12, s40, s10
	v_readlane_b32 s10, v254, 19
	v_and_b32_e32 v163, 15, v162
	v_and_b32_e32 v2, 48, v162
	v_lshlrev_b32_e32 v3, 2, v162
	s_add_u32 s14, s4, s10
	s_and_b32 s18, s24, 3
	s_lshl_b32 s10, s11, 13
	v_lshl_or_b32 v2, v163, 6, v2
	v_and_b32_e32 v3, 32, v3
	v_bitop3_b32 v4, v2, s10, v3 bitop3:0xde
	s_lshl_b32 s10, s18, 12
	s_add_i32 s60, s19, 0x18000
	v_bitop3_b32 v3, v2, s10, v3 bitop3:0xde
	s_mov_b32 s42, s6
	s_mov_b32 s43, s7
	s_mov_b32 m0, s60
	v_readlane_b32 s10, v254, 18
	s_add_i32 s61, s19, 0x1a000
	s_add_i32 s62, s19, 0x8000
	s_add_i32 s63, s19, 0xa000
	s_nop 0
	buffer_load_dwordx4 v0, s[40:43], s10 offen lds
	s_mov_b32 m0, s61
	s_add_i32 s66, s19, 0x1c000
	buffer_load_dwordx4 v130, s[40:43], s10 offen lds
	s_mov_b32 m0, s62
	v_readlane_b32 s10, v254, 20
	s_add_i32 s67, s19, 0x1e000
	v_mov_b32_e32 v2, 0
	v_readlane_b32 s16, v254, 34
	s_mov_b32 s53, s27
	v_lshl_or_b32 v165, s11, 6, v163
	buffer_load_dwordx4 v0, s[4:7], s10 offen lds
	s_mov_b32 m0, s63
	s_add_i32 s68, s19, 0xc000
	buffer_load_dwordx4 v130, s[4:7], s10 offen lds
	s_mov_b32 m0, s66
	v_readlane_b32 s10, v254, 22
	s_add_i32 s69, s19, 0xe000
	s_mov_b32 s72, 0
	s_sub_i32 s71, 0, s4
	v_add_u32_e32 v131, 0, v3
	v_add_u32_e32 v132, 0, v4
	buffer_load_dwordx4 v0, s[40:43], s10 offen lds
	s_mov_b32 m0, s67
	s_mov_b32 s25, s16
	buffer_load_dwordx4 v130, s[40:43], s10 offen lds
	s_waitcnt vmcnt(8)
	s_barrier
	s_waitcnt vmcnt(6)
	v_readlane_b32 s10, v254, 15
	v_mov_b32_e32 v3, v2
	v_mov_b32_e32 v4, v2
	v_mov_b32_e32 v5, v2
	v_mov_b32_e32 v10, v2
	v_mov_b32_e32 v11, v2
	v_mov_b32_e32 v12, v2
	v_mov_b32_e32 v13, v2
	v_mov_b32_e32 v34, v2
	v_mov_b32_e32 v35, v2
	v_mov_b32_e32 v36, v2
	v_mov_b32_e32 v37, v2
	v_mov_b32_e32 v58, v2
	v_mov_b32_e32 v59, v2
	v_mov_b32_e32 v60, v2
	v_mov_b32_e32 v61, v2
	v_mov_b32_e32 v86, v2
	v_mov_b32_e32 v87, v2
	v_mov_b32_e32 v88, v2
	v_mov_b32_e32 v89, v2
	v_mov_b32_e32 v66, v2
	v_mov_b32_e32 v67, v2
	v_mov_b32_e32 v68, v2
	v_mov_b32_e32 v69, v2
	v_mov_b32_e32 v30, v2
	v_mov_b32_e32 v31, v2
	v_mov_b32_e32 v32, v2
	v_mov_b32_e32 v33, v2
	v_mov_b32_e32 v42, v2
	v_mov_b32_e32 v43, v2
	v_mov_b32_e32 v44, v2
	v_mov_b32_e32 v45, v2
	v_mov_b32_e32 v26, v2
	v_mov_b32_e32 v27, v2
	v_mov_b32_e32 v28, v2
	v_mov_b32_e32 v29, v2
	v_mov_b32_e32 v38, v2
	v_mov_b32_e32 v39, v2
	v_mov_b32_e32 v40, v2
	v_mov_b32_e32 v41, v2
	v_mov_b32_e32 v90, v2
	v_mov_b32_e32 v91, v2
	v_mov_b32_e32 v92, v2
	v_mov_b32_e32 v93, v2
	v_mov_b32_e32 v94, v2
	v_mov_b32_e32 v95, v2
	v_mov_b32_e32 v96, v2
	v_mov_b32_e32 v97, v2
	v_mov_b32_e32 v70, v2
	v_mov_b32_e32 v71, v2
	v_mov_b32_e32 v72, v2
	v_mov_b32_e32 v73, v2
	v_mov_b32_e32 v82, v2
	v_mov_b32_e32 v83, v2
	v_mov_b32_e32 v84, v2
	v_mov_b32_e32 v85, v2
	v_mov_b32_e32 v46, v2
	v_mov_b32_e32 v47, v2
	v_mov_b32_e32 v48, v2
	v_mov_b32_e32 v49, v2
	v_mov_b32_e32 v62, v2
	v_mov_b32_e32 v63, v2
	v_mov_b32_e32 v64, v2
	v_mov_b32_e32 v65, v2
	v_mov_b32_e32 v126, v2
	v_mov_b32_e32 v127, v2
	v_mov_b32_e32 v128, v2
	v_mov_b32_e32 v129, v2
	v_mov_b32_e32 v114, v2
	v_mov_b32_e32 v115, v2
	v_mov_b32_e32 v116, v2
	v_mov_b32_e32 v117, v2
	v_mov_b32_e32 v110, v2
	v_mov_b32_e32 v111, v2
	v_mov_b32_e32 v112, v2
	v_mov_b32_e32 v113, v2
	v_mov_b32_e32 v98, v2
	v_mov_b32_e32 v99, v2
	v_mov_b32_e32 v100, v2
	v_mov_b32_e32 v101, v2
	v_mov_b32_e32 v78, v2
	v_mov_b32_e32 v79, v2
	v_mov_b32_e32 v80, v2
	v_mov_b32_e32 v81, v2
	v_mov_b32_e32 v50, v2
	v_mov_b32_e32 v51, v2
	v_mov_b32_e32 v52, v2
	v_mov_b32_e32 v53, v2
	v_mov_b32_e32 v18, v2
	v_mov_b32_e32 v19, v2
	v_mov_b32_e32 v20, v2
	v_mov_b32_e32 v21, v2
	v_mov_b32_e32 v6, v2
	v_mov_b32_e32 v7, v2
	v_mov_b32_e32 v8, v2
	v_mov_b32_e32 v9, v2
	v_mov_b32_e32 v118, v2
	v_mov_b32_e32 v119, v2
	v_mov_b32_e32 v120, v2
	v_mov_b32_e32 v121, v2
	v_mov_b32_e32 v122, v2
	v_mov_b32_e32 v123, v2
	v_mov_b32_e32 v124, v2
	v_mov_b32_e32 v125, v2
	v_mov_b32_e32 v102, v2
	v_mov_b32_e32 v103, v2
	v_mov_b32_e32 v104, v2
	v_mov_b32_e32 v105, v2
	v_mov_b32_e32 v106, v2
	v_mov_b32_e32 v107, v2
	v_mov_b32_e32 v108, v2
	v_mov_b32_e32 v109, v2
	v_mov_b32_e32 v54, v2
	v_mov_b32_e32 v55, v2
	v_mov_b32_e32 v56, v2
	v_mov_b32_e32 v57, v2
	v_mov_b32_e32 v74, v2
	v_mov_b32_e32 v75, v2
	v_mov_b32_e32 v76, v2
	v_mov_b32_e32 v77, v2
	v_mov_b32_e32 v14, v2
	v_mov_b32_e32 v15, v2
	v_mov_b32_e32 v16, v2
	v_mov_b32_e32 v17, v2
	v_mov_b32_e32 v22, v2
	v_mov_b32_e32 v23, v2
	v_mov_b32_e32 v24, v2
	v_mov_b32_e32 v25, v2
	s_barrier
	v_readlane_b32 s17, v254, 35
	s_branch .LBB0_1573
